# v20 + the row-factor part of the fold phases runs on workgroups 64..127 so it overlaps the partial-tile fold on workgroups 0..31
# speedup vs baseline: 1.0069x; 1.0020x over previous
; __device__ __forceinline__ float row_rs(const float* ssq, int row) {
;     const f32x4* q = (const f32x4*)(ssq + (size_t)row * 16); const f32x4 a = q[0], b = q[1], c = q[2], d = q[3];
; __device__ void fold_rows(const Params& p, int nslice, const float* ssq, float* rsv) {
;     ...
;     for (int row = p.bid * 512 + t_; row < MP - 256; row += p.nblk * 512) rsv[row] = row_rs(ssq, row);
.LBB0_173:
	s_or_b64 exec, exec, s[42:43]
	s_add_i32 s22, s29, 0xc0
	s_and_b32 s22, s22, 0xff
	v_lshl_add_u32 v2, s22, 9, v0
	s_mov_b32 s22, 0x8000
	s_mov_b32 s33, s29
	v_cmp_gt_i32_e32 vcc, s22, v2
	s_and_saveexec_b64 s[40:41], vcc
	s_movk_i32 s29, 0x7fff
	s_mov_b32 s30, 0x800000
	s_cbranch_execz .LBB0_176
	s_lshl_b32 s42, s39, 9
	s_waitcnt lgkmcnt(0)
	v_ashrrev_i32_e32 v3, 31, v2
	s_ashr_i32 s43, s42, 31
	v_lshlrev_b64 v[6:7], 6, v[2:3]
	v_lshl_add_u64 v[4:5], v[2:3], 2, s[82:83]
	s_lshl_b64 s[44:45], s[42:43], 2
	v_lshl_add_u64 v[6:7], s[4:5], 0, v[6:7]
	s_lshl_b64 s[56:57], s[42:43], 6
	s_mov_b64 s[58:59], 0

; __device__ __forceinline__ float row_rs(const float* ssq, int row) {
;     const f32x4* q = (const f32x4*)(ssq + (size_t)row * 16); const f32x4 a = q[0], b = q[1], c = q[2], d = q[3];
; __device__ void fold_rows(const Params& p, int nslice, const float* ssq, float* rsv) {
;     ...
;     for (int row = p.bid * 512 + t_; row < MP - 256; row += p.nblk * 512) rsv[row] = row_rs(ssq, row);
.LBB0_854:
	s_or_b64 exec, exec, s[14:15]
	s_add_i32 s14, s29, 0xc0
	s_and_b32 s14, s14, 0xff
	v_lshl_add_u32 v2, s14, 9, v0
	s_mov_b32 s14, 0x8000
	s_mov_b32 s33, s29
	v_cmp_gt_i32_e32 vcc, s14, v2
	s_and_saveexec_b64 s[14:15], vcc
	s_movk_i32 s29, 0x7fff
	s_mov_b32 s30, 0x800000
	s_cbranch_execz .LBB0_857
	s_lshl_b32 s22, s39, 9
	s_waitcnt lgkmcnt(0)
	v_ashrrev_i32_e32 v3, 31, v2
	s_ashr_i32 s23, s22, 31
	v_lshlrev_b64 v[6:7], 6, v[2:3]
	v_lshl_add_u64 v[4:5], v[2:3], 2, s[10:11]
	s_lshl_b64 s[10:11], s[22:23], 2
	v_lshl_add_u64 v[6:7], s[84:85], 0, v[6:7]
	s_lshl_b64 s[20:21], s[22:23], 6
	s_mov_b64 s[42:43], 0
